# P6 K loop: in-loop copy address block spread 2 instructions per MFMA gap across phase 0's burst instead of one contiguous run
# speedup vs baseline: 1.0179x; 1.0127x over previous
.LBB0_740:
	ds_read_b128 v[44:47], v205
	ds_read_b128 v[48:51], v205 offset:1024
	ds_read_b128 v[52:55], v205 offset:2048
	ds_read_b128 v[56:59], v205 offset:3072
	ds_read_b128 v[60:63], v206
	ds_read_b128 v[64:67], v206 offset:1024
	ds_read_b128 v[68:71], v206 offset:2048
	ds_read_b128 v[160:163], v206 offset:3072
	s_add_u32 s12, s10, s8
	s_addc_u32 s13, s11, s9
	s_add_u32 s12, s12, 0x100
	s_addc_u32 s13, s13, 0
	s_add_u32 s63, s19, s8
	s_addc_u32 vcc_lo, s55, s9
	s_cmpk_eq_i32 s8, 0x700
	s_cselect_b32 s15, s59, s13
	s_cselect_b32 s14, s58, s12
	s_cselect_b32 s4, s57, s1
	s_cselect_b32 s5, s56, s0
	s_cselect_b32 s13, s3, vcc_lo
	s_cselect_b32 s12, s18, s63
	s_cselect_b32 s63, s97, s17
	v_lshl_add_u64 v[224:225], v[42:43], 0, s[8:9]
	s_add_i32 m0, s65, 0xc000
	ds_read_b128 v[164:167], v207
	ds_read_b128 v[168:171], v207 offset:1024
	ds_read_b128 v[172:175], v207 offset:2048
	ds_read_b128 v[194:197], v207 offset:3072
	ds_read_b128 v[198:201], v207 offset:4096
	ds_read_b128 v[210:213], v207 offset:5120
	ds_read_b128 v[214:217], v207 offset:6144
	ds_read_b128 v[218:221], v207 offset:7168
	global_load_lds_dwordx4 v[224:225], off
	v_lshl_add_u64 v[224:225], v[40:41], 0, s[8:9]
	s_add_i32 m0, s65, 0xe000
	s_nop 0
	global_load_lds_dwordx4 v[224:225], off
	s_waitcnt vmcnt(8)
	s_waitcnt lgkmcnt(0)
	s_barrier
	s_setprio 1
	s_waitcnt lgkmcnt(0)
	v_mfma_f32_16x16x32_bf16 v[156:159], v[44:47], v[164:167], v[156:159]
	v_mfma_f32_16x16x32_bf16 v[152:155], v[52:55], v[164:167], v[152:155]
	v_mfma_f32_16x16x32_bf16 v[140:143], v[44:47], v[172:175], v[140:143]
	v_mfma_f32_16x16x32_bf16 v[136:139], v[52:55], v[172:175], v[136:139]
	v_mfma_f32_16x16x32_bf16 v[124:127], v[44:47], v[198:201], v[124:127]
	v_mfma_f32_16x16x32_bf16 v[120:123], v[52:55], v[198:201], v[120:123]
	v_readlane_b32 s32, v247, 60
	v_mfma_f32_16x16x32_bf16 v[108:111], v[44:47], v[214:217], v[108:111]
	s_add_i32 s32, s32, -1
	v_readlane_b32 s100, v247, 61
	v_mfma_f32_16x16x32_bf16 v[104:107], v[52:55], v[214:217], v[104:107]
	s_min_u32 s32, s32, s100
	v_readlane_b32 s100, v247, 62
	v_mfma_f32_16x16x32_bf16 v[156:159], v[48:51], v[168:171], v[156:159]
	s_add_i32 s32, s32, s100
	s_min_u32 s32, s32, 0x2f6f
	v_mfma_f32_16x16x32_bf16 v[152:155], v[56:59], v[168:171], v[152:155]
	s_lshr_b32 s100, s32, 1
	s_add_i32 s100, s100, 0x2808
	v_mfma_f32_16x16x32_bf16 v[140:143], v[48:51], v[194:197], v[140:143]
	s_mul_i32 s101, s100, 0x8081
	s_lshr_b32 s101, s101, 24
	v_mfma_f32_16x16x32_bf16 v[136:139], v[56:59], v[194:197], v[136:139]
	s_mul_i32 s98, s101, 0x1fe
	s_sub_i32 s100, s100, s98
	v_mfma_f32_16x16x32_bf16 v[124:127], v[48:51], v[210:213], v[124:127]
	s_lshl_b32 s101, s101, 22
	s_lshl_b32 s100, s100, 13
	v_mfma_f32_16x16x32_bf16 v[120:123], v[56:59], v[210:213], v[120:123]
	s_add_u32 s100, s100, s101
	s_bitcmp1_b32 s32, 0
	v_mfma_f32_16x16x32_bf16 v[108:111], v[48:51], v[218:221], v[108:111]
	s_cselect_b32 s98, s66, s70
	s_cselect_b32 s99, s67, s71
	v_mfma_f32_16x16x32_bf16 v[104:107], v[56:59], v[218:221], v[104:107]
	s_add_u32 s98, s98, s100
	s_addc_u32 s99, s99, 0
	s_setprio 0
	s_setprio 1
	v_mfma_f32_16x16x32_bf16 v[148:151], v[60:63], v[164:167], v[148:151]
	v_lshlrev_b32_e32 v236, 4, v222
	global_store_dwordx4 v236, v[252:255], s[98:99] nt
	v_mfma_f32_16x16x32_bf16 v[144:147], v[68:71], v[164:167], v[144:147]
	v_readlane_b32 s32, v247, 60
	v_readlane_b32 s100, v247, 61
	v_mfma_f32_16x16x32_bf16 v[132:135], v[60:63], v[172:175], v[132:135]
	s_min_u32 s32, s32, s100
	v_readlane_b32 s100, v247, 62
	v_mfma_f32_16x16x32_bf16 v[128:131], v[68:71], v[172:175], v[128:131]
	s_add_i32 s32, s32, s100
	s_min_u32 s32, s32, 0x2f6f
	v_mfma_f32_16x16x32_bf16 v[116:119], v[60:63], v[198:201], v[116:119]
	s_lshr_b32 s100, s32, 1
	s_add_i32 s100, s100, 0x2808
	v_mfma_f32_16x16x32_bf16 v[112:115], v[68:71], v[198:201], v[112:115]
	s_mul_i32 s101, s100, 0x8081
	s_lshr_b32 s101, s101, 24
	v_mfma_f32_16x16x32_bf16 v[100:103], v[60:63], v[214:217], v[100:103]
	s_mul_i32 s98, s101, 0x1fe
	s_sub_i32 s100, s100, s98
	v_mfma_f32_16x16x32_bf16 v[96:99], v[68:71], v[214:217], v[96:99]
	s_lshl_b32 s101, s101, 22
	s_lshl_b32 s100, s100, 13
	v_mfma_f32_16x16x32_bf16 v[148:151], v[64:67], v[168:171], v[148:151]
	s_add_u32 s100, s100, s101
	s_bitcmp1_b32 s32, 0
	v_mfma_f32_16x16x32_bf16 v[144:147], v[160:163], v[168:171], v[144:147]
	s_cselect_b32 s98, s84, s82
	s_cselect_b32 s99, s85, s83
	v_mfma_f32_16x16x32_bf16 v[132:135], v[64:67], v[194:197], v[132:135]
	s_add_u32 s98, s98, s100
	s_addc_u32 s99, s99, 0
	v_mfma_f32_16x16x32_bf16 v[128:131], v[160:163], v[194:197], v[128:131]
	s_add_u32 s98, s98, 0x4000
	s_addc_u32 s99, s99, 0
	v_mfma_f32_16x16x32_bf16 v[116:119], v[64:67], v[210:213], v[116:119]
	v_lshlrev_b32_e32 v236, 4, v222
	global_load_dwordx4 v[252:255], v236, s[98:99] nt
	v_mfma_f32_16x16x32_bf16 v[112:115], v[160:163], v[210:213], v[112:115]
	v_readlane_b32 s32, v247, 60
	s_add_i32 s32, s32, 1
	v_mfma_f32_16x16x32_bf16 v[100:103], v[64:67], v[218:221], v[100:103]
	v_writelane_b32 v247, s32, 60
	s_nop 0
	v_mfma_f32_16x16x32_bf16 v[96:99], v[160:163], v[218:221], v[96:99]
	s_setprio 0
	s_barrier
	s_add_i32 vcc_lo, s88, s33
	v_lshl_add_u64 v[228:229], s[12:13], 0, v[178:179]
	s_mov_b32 m0, vcc_lo
	ds_read_b128 v[164:167], v207 offset:16384
	ds_read_b128 v[168:171], v207 offset:17408
	ds_read_b128 v[172:175], v207 offset:18432
	ds_read_b128 v[194:197], v207 offset:19456
	ds_read_b128 v[198:201], v207 offset:20480
	ds_read_b128 v[210:213], v207 offset:21504
	ds_read_b128 v[214:217], v207 offset:22528
	ds_read_b128 v[218:221], v207 offset:23552
	global_load_lds_dwordx4 v[228:229], off
	s_add_i32 m0, vcc_lo, 0x2000
	s_add_u32 vcc_lo, s12, 0x40000
	v_lshl_add_u64 v[230:231], s[12:13], 0, v[182:183]
	s_addc_u32 vcc_hi, s13, 0
	s_add_i32 s36, s89, s33
	global_load_lds_dwordx4 v[230:231], off
	v_lshl_add_u64 v[224:225], vcc, 0, v[178:179]
	s_mov_b32 m0, s36
	v_lshl_add_u64 v[232:233], s[14:15], 0, v[176:177]
	global_load_lds_dwordx4 v[224:225], off
	s_add_i32 m0, s36, 0x2000
	v_lshl_add_u64 v[224:225], vcc, 0, v[182:183]
	s_sub_u32 vcc_lo, 0, s63
	global_load_lds_dwordx4 v[224:225], off
	s_mov_b32 m0, s65
	v_lshl_add_u64 v[224:225], s[14:15], 0, v[180:181]
	s_subb_u32 vcc_hi, 0, 0
	global_load_lds_dwordx4 v[232:233], off
	v_lshl_add_u64 v[234:235], v[224:225], 0, vcc
	s_mov_b32 m0, s68
	s_nop 0
	global_load_lds_dwordx4 v[234:235], off
	s_waitcnt vmcnt(10)
	s_waitcnt lgkmcnt(0)
	s_barrier
	s_setprio 1
	s_waitcnt lgkmcnt(0)
	v_mfma_f32_16x16x32_bf16 v[92:95], v[44:47], v[164:167], v[92:95]
	v_mfma_f32_16x16x32_bf16 v[88:91], v[52:55], v[164:167], v[88:91]
	v_mfma_f32_16x16x32_bf16 v[76:79], v[44:47], v[172:175], v[76:79]
	v_mfma_f32_16x16x32_bf16 v[72:75], v[52:55], v[172:175], v[72:75]
	v_mfma_f32_16x16x32_bf16 v[28:31], v[44:47], v[198:201], v[28:31]
	v_mfma_f32_16x16x32_bf16 v[24:27], v[52:55], v[198:201], v[24:27]
	v_mfma_f32_16x16x32_bf16 v[12:15], v[44:47], v[214:217], v[12:15]
	v_mfma_f32_16x16x32_bf16 v[8:11], v[52:55], v[214:217], v[8:11]
	v_mfma_f32_16x16x32_bf16 v[92:95], v[48:51], v[168:171], v[92:95]
	v_mfma_f32_16x16x32_bf16 v[88:91], v[56:59], v[168:171], v[88:91]
	v_mfma_f32_16x16x32_bf16 v[76:79], v[48:51], v[194:197], v[76:79]
	v_mfma_f32_16x16x32_bf16 v[72:75], v[56:59], v[194:197], v[72:75]
	v_mfma_f32_16x16x32_bf16 v[28:31], v[48:51], v[210:213], v[28:31]
	v_mfma_f32_16x16x32_bf16 v[24:27], v[56:59], v[210:213], v[24:27]
	v_mfma_f32_16x16x32_bf16 v[12:15], v[48:51], v[218:221], v[12:15]
	v_mfma_f32_16x16x32_bf16 v[8:11], v[56:59], v[218:221], v[8:11]
	s_setprio 0
	s_setprio 1
	v_mfma_f32_16x16x32_bf16 v[36:39], v[60:63], v[172:175], v[36:39]
	v_mfma_f32_16x16x32_bf16 v[32:35], v[68:71], v[172:175], v[32:35]
	v_mfma_f32_16x16x32_bf16 v[20:23], v[60:63], v[198:201], v[20:23]
	v_mfma_f32_16x16x32_bf16 v[16:19], v[68:71], v[198:201], v[16:19]
	v_mfma_f32_16x16x32_bf16 v[4:7], v[60:63], v[214:217], v[4:7]
	v_mfma_f32_16x16x32_bf16 v[0:3], v[68:71], v[214:217], v[0:3]
	v_mfma_f32_16x16x32_bf16 v[44:47], v[60:63], v[164:167], v[84:87]
	v_mfma_f32_16x16x32_bf16 v[48:51], v[68:71], v[164:167], v[80:83]
	v_mfma_f32_16x16x32_bf16 v[36:39], v[64:67], v[194:197], v[36:39]
	v_mfma_f32_16x16x32_bf16 v[32:35], v[160:163], v[194:197], v[32:35]
	v_mfma_f32_16x16x32_bf16 v[20:23], v[64:67], v[210:213], v[20:23]
	v_mfma_f32_16x16x32_bf16 v[16:19], v[160:163], v[210:213], v[16:19]
	v_mfma_f32_16x16x32_bf16 v[4:7], v[64:67], v[218:221], v[4:7]
	v_mfma_f32_16x16x32_bf16 v[0:3], v[160:163], v[218:221], v[0:3]
	v_mfma_f32_16x16x32_bf16 v[44:47], v[64:67], v[168:171], v[44:47]
	v_mfma_f32_16x16x32_bf16 v[48:51], v[160:163], v[168:171], v[48:51]
	s_setprio 0
	s_barrier
	s_add_i32 s36, 0, 0x18000
	s_add_i32 s37, 0, 0x1c000
	v_add_u32_e32 v64, s36, v204
	v_add_u32_e32 v80, s37, v204
	ds_read_b128 v[52:55], v64
	ds_read_b128 v[56:59], v64 offset:1024
	ds_read_b128 v[60:63], v64 offset:2048
	ds_read_b128 v[64:67], v64 offset:3072
	ds_read_b128 v[68:71], v80
	ds_read_b128 v[160:163], v80 offset:1024
	ds_read_b128 v[164:167], v80 offset:2048
	ds_read_b128 v[168:171], v80 offset:3072
	s_add_u32 s14, s14, s5
	s_addc_u32 s15, s15, s4
	s_mov_b32 m0, s69
	v_lshl_add_u64 v[224:225], s[14:15], 0, v[176:177]
	ds_read_b128 v[80:83], v207 offset:32768
	ds_read_b128 v[84:87], v207 offset:33792
	ds_read_b128 v[172:175], v207 offset:34816
	ds_read_b128 v[194:197], v207 offset:35840
	ds_read_b128 v[198:201], v207 offset:36864
	ds_read_b128 v[210:213], v207 offset:37888
	ds_read_b128 v[214:217], v207 offset:38912
	ds_read_b128 v[218:221], v207 offset:39936
	global_load_lds_dwordx4 v[224:225], off
	v_lshl_add_u64 v[224:225], s[14:15], 0, v[180:181]
	v_lshl_add_u64 v[224:225], v[224:225], 0, vcc
	s_mov_b32 m0, s72
	s_nop 0
	global_load_lds_dwordx4 v[224:225], off
	s_waitcnt vmcnt(10)
	s_waitcnt lgkmcnt(0)
	s_barrier
	s_setprio 1
	s_waitcnt lgkmcnt(0)
	v_mfma_f32_16x16x32_bf16 v[156:159], v[52:55], v[80:83], v[156:159]
	v_mfma_f32_16x16x32_bf16 v[152:155], v[60:63], v[80:83], v[152:155]
	v_mfma_f32_16x16x32_bf16 v[140:143], v[52:55], v[172:175], v[140:143]
	v_mfma_f32_16x16x32_bf16 v[136:139], v[60:63], v[172:175], v[136:139]
	v_mfma_f32_16x16x32_bf16 v[124:127], v[52:55], v[198:201], v[124:127]
	v_mfma_f32_16x16x32_bf16 v[120:123], v[60:63], v[198:201], v[120:123]
	v_mfma_f32_16x16x32_bf16 v[108:111], v[52:55], v[214:217], v[108:111]
	v_mfma_f32_16x16x32_bf16 v[104:107], v[60:63], v[214:217], v[104:107]
	v_mfma_f32_16x16x32_bf16 v[156:159], v[56:59], v[84:87], v[156:159]
	v_mfma_f32_16x16x32_bf16 v[152:155], v[64:67], v[84:87], v[152:155]
	v_mfma_f32_16x16x32_bf16 v[140:143], v[56:59], v[194:197], v[140:143]
	v_mfma_f32_16x16x32_bf16 v[136:139], v[64:67], v[194:197], v[136:139]
	v_mfma_f32_16x16x32_bf16 v[124:127], v[56:59], v[210:213], v[124:127]
	v_mfma_f32_16x16x32_bf16 v[120:123], v[64:67], v[210:213], v[120:123]
	v_mfma_f32_16x16x32_bf16 v[108:111], v[56:59], v[218:221], v[108:111]
	v_mfma_f32_16x16x32_bf16 v[104:107], v[64:67], v[218:221], v[104:107]
	s_setprio 0
	s_setprio 1
	v_mfma_f32_16x16x32_bf16 v[148:151], v[68:71], v[80:83], v[148:151]
	v_mfma_f32_16x16x32_bf16 v[80:83], v[164:167], v[80:83], v[144:147]
	v_mfma_f32_16x16x32_bf16 v[144:147], v[168:171], v[84:87], v[80:83]
	v_mfma_f32_16x16x32_bf16 v[80:83], v[68:71], v[172:175], v[132:135]
	v_mfma_f32_16x16x32_bf16 v[132:135], v[160:163], v[194:197], v[80:83]
	v_mfma_f32_16x16x32_bf16 v[80:83], v[164:167], v[172:175], v[128:131]
	v_mfma_f32_16x16x32_bf16 v[128:131], v[168:171], v[194:197], v[80:83]
	v_mfma_f32_16x16x32_bf16 v[80:83], v[68:71], v[198:201], v[116:119]
	v_mfma_f32_16x16x32_bf16 v[116:119], v[160:163], v[210:213], v[80:83]
	v_mfma_f32_16x16x32_bf16 v[80:83], v[164:167], v[198:201], v[112:115]
	v_mfma_f32_16x16x32_bf16 v[112:115], v[168:171], v[210:213], v[80:83]
	v_mfma_f32_16x16x32_bf16 v[80:83], v[68:71], v[214:217], v[100:103]
	v_mfma_f32_16x16x32_bf16 v[100:103], v[160:163], v[218:221], v[80:83]
	v_mfma_f32_16x16x32_bf16 v[80:83], v[164:167], v[214:217], v[96:99]
	v_mfma_f32_16x16x32_bf16 v[148:151], v[160:163], v[84:87], v[148:151]
	v_mfma_f32_16x16x32_bf16 v[96:99], v[168:171], v[218:221], v[80:83]
	s_setprio 0
	s_barrier
	s_add_i32 s4, s36, s33
	v_lshl_add_u64 v[84:85], v[228:229], 0, s[50:51]
	s_mov_b32 m0, s4
	s_nop 0
	ds_read_b128 v[80:83], v207 offset:49152
	ds_read_b128 v[172:175], v207 offset:50176
	ds_read_b128 v[194:197], v207 offset:51200
	ds_read_b128 v[198:201], v207 offset:52224
	ds_read_b128 v[210:213], v207 offset:53248
	ds_read_b128 v[214:217], v207 offset:54272
	ds_read_b128 v[218:221], v207 offset:55296
	ds_read_b128 v[224:227], v207 offset:56320
	global_load_lds_dwordx4 v[84:85], off
	s_add_i32 m0, s4, 0x2000
	s_add_u32 s12, s12, 0x40080
	v_lshl_add_u64 v[84:85], v[230:231], 0, s[50:51]
	s_addc_u32 s13, s13, 0
	s_add_i32 s4, s37, s33
	global_load_lds_dwordx4 v[84:85], off
	v_lshl_add_u64 v[84:85], s[12:13], 0, v[178:179]
	s_mov_b32 m0, s4
	s_nop 0
	global_load_lds_dwordx4 v[84:85], off
	v_lshl_add_u64 v[84:85], s[12:13], 0, v[182:183]
	s_add_i32 m0, s4, 0x2000
	s_nop 0
	global_load_lds_dwordx4 v[84:85], off
	v_lshl_add_u64 v[84:85], v[232:233], 0, s[50:51]
	s_mov_b32 m0, s75
	s_nop 0
	global_load_lds_dwordx4 v[84:85], off
	v_lshl_add_u64 v[84:85], v[234:235], 0, s[50:51]
	s_mov_b32 m0, s76
	s_nop 0
	global_load_lds_dwordx4 v[84:85], off
	s_waitcnt vmcnt(8)
	s_waitcnt lgkmcnt(0)
	s_barrier
	s_setprio 1
	s_waitcnt lgkmcnt(0)
	v_mfma_f32_16x16x32_bf16 v[84:87], v[52:55], v[80:83], v[92:95]
	v_mfma_f32_16x16x32_bf16 v[92:95], v[56:59], v[172:175], v[84:87]
	v_mfma_f32_16x16x32_bf16 v[84:87], v[60:63], v[80:83], v[88:91]
	v_mfma_f32_16x16x32_bf16 v[76:79], v[52:55], v[194:197], v[76:79]
	v_mfma_f32_16x16x32_bf16 v[72:75], v[60:63], v[194:197], v[72:75]
	v_mfma_f32_16x16x32_bf16 v[28:31], v[52:55], v[210:213], v[28:31]
	v_mfma_f32_16x16x32_bf16 v[24:27], v[60:63], v[210:213], v[24:27]
	v_mfma_f32_16x16x32_bf16 v[12:15], v[52:55], v[218:221], v[12:15]
	v_mfma_f32_16x16x32_bf16 v[8:11], v[60:63], v[218:221], v[8:11]
	v_mfma_f32_16x16x32_bf16 v[88:91], v[64:67], v[172:175], v[84:87]
	v_mfma_f32_16x16x32_bf16 v[76:79], v[56:59], v[198:201], v[76:79]
	v_mfma_f32_16x16x32_bf16 v[72:75], v[64:67], v[198:201], v[72:75]
	v_mfma_f32_16x16x32_bf16 v[28:31], v[56:59], v[214:217], v[28:31]
	v_mfma_f32_16x16x32_bf16 v[24:27], v[64:67], v[214:217], v[24:27]
	v_mfma_f32_16x16x32_bf16 v[12:15], v[56:59], v[224:227], v[12:15]
	v_mfma_f32_16x16x32_bf16 v[8:11], v[64:67], v[224:227], v[8:11]
	s_setprio 0
	s_setprio 1
	v_mfma_f32_16x16x32_bf16 v[44:47], v[68:71], v[80:83], v[44:47]
	v_mfma_f32_16x16x32_bf16 v[84:87], v[160:163], v[172:175], v[44:47]
	v_mfma_f32_16x16x32_bf16 v[44:47], v[164:167], v[80:83], v[48:51]
	v_mfma_f32_16x16x32_bf16 v[36:39], v[68:71], v[194:197], v[36:39]
	v_mfma_f32_16x16x32_bf16 v[32:35], v[164:167], v[194:197], v[32:35]
	v_mfma_f32_16x16x32_bf16 v[20:23], v[68:71], v[210:213], v[20:23]
	v_mfma_f32_16x16x32_bf16 v[16:19], v[164:167], v[210:213], v[16:19]
	v_mfma_f32_16x16x32_bf16 v[4:7], v[68:71], v[218:221], v[4:7]
	v_mfma_f32_16x16x32_bf16 v[0:3], v[164:167], v[218:221], v[0:3]
	v_mfma_f32_16x16x32_bf16 v[80:83], v[168:171], v[172:175], v[44:47]
	v_mfma_f32_16x16x32_bf16 v[36:39], v[160:163], v[198:201], v[36:39]
	v_mfma_f32_16x16x32_bf16 v[32:35], v[168:171], v[198:201], v[32:35]
	v_mfma_f32_16x16x32_bf16 v[20:23], v[160:163], v[214:217], v[20:23]
	v_mfma_f32_16x16x32_bf16 v[16:19], v[168:171], v[214:217], v[16:19]
	v_mfma_f32_16x16x32_bf16 v[4:7], v[160:163], v[224:227], v[4:7]
	v_mfma_f32_16x16x32_bf16 v[0:3], v[168:171], v[224:227], v[0:3]
	s_setprio 0
	s_barrier
	s_add_i32 s62, s62, 2
	s_add_u32 s8, s8, 0x100
	s_addc_u32 s9, s9, 0
	s_cmp_gt_u32 s62, 13
	s_cbranch_scc0 .LBB0_740
	s_and_b64 vcc, exec, s[52:53]
	s_cbranch_vccz .LBB0_743
	s_barrier
